# g1 item stream rotated to (blockIdx+384)%grid so remainder items avoid the CU partners of q-up remainder blocks
# speedup vs baseline: 1.0023x; 1.0023x over previous
.LBB0_84:
	s_or_b64 exec, exec, s[0:1]
	v_readlane_b32 s20, v252, 0
	s_cmpk_lt_i32 s20, 0x500
	s_cselect_b64 s[0:1], -1, 0
	s_add_u32 s34, s48, 0x800000
	s_addc_u32 s35, s49, 0
	v_writelane_b32 v252, s0, 19
	s_cmpk_lt_i32 s20, 0x4e0
	s_waitcnt lgkmcnt(0)
	v_cvt_f32_u32_e32 v0, s50
	v_writelane_b32 v252, s1, 20
	s_cselect_b64 s[0:1], -1, 0
	v_writelane_b32 v252, s0, 21
	v_rcp_iflag_f32_e32 v0, v0
	v_mov_b32_e32 v1, 0
	v_writelane_b32 v252, s1, 22
	s_add_u32 s0, s48, 0x7c0000
	s_addc_u32 s1, s49, 0
	v_writelane_b32 v252, s0, 23
	s_add_u32 s16, s48, 0x740000
	s_addc_u32 s17, s49, 0
	v_writelane_b32 v252, s1, 24
	s_add_u32 s18, s48, 0x620000
	v_readlane_b32 s0, v252, 25
	s_addc_u32 s19, s49, 0
	v_readlane_b32 s4, v252, 29
	v_readlane_b32 s5, v252, 30
	v_readlane_b32 s1, v252, 26
	v_readlane_b32 s2, v252, 27
	v_readlane_b32 s3, v252, 28
	s_cmp_lg_u64 s[4:5], 0
	s_cselect_b64 s[2:3], -1, 0
	s_cmp_lg_u64 s[0:1], 0
	s_cselect_b64 s[0:1], -1, 0
	s_add_u32 s36, s48, 0xa00000
	s_addc_u32 s37, s49, 0
	s_add_u32 s38, s48, 0xb3c000
	s_addc_u32 s39, s49, 0
	v_readlane_b32 s10, v252, 35
	s_add_u32 s40, s48, 0x133c000
	s_addc_u32 s41, s49, 0
	s_lshl_b32 s42, s50, 2
	s_lshl_b32 s10, s20, 2
	s_add_u32 s44, s48, 0xed7c200
	s_addc_u32 s45, s49, 0
	s_add_u32 s46, s48, 0xed7c400
	s_addc_u32 s47, s49, 0
	s_add_u32 s58, s48, 0xed7c500
	s_addc_u32 s59, s49, 0
	s_add_u32 s76, s48, 0xed7c600
	s_addc_u32 s77, s49, 0
	s_add_u32 s78, s48, 0xed7c700
	s_addc_u32 s79, s49, 0
	s_add_u32 s80, s48, 0xed7c800
	s_addc_u32 s81, s49, 0
	s_add_u32 s82, s48, 0xed7c900
	s_addc_u32 s83, s49, 0
	s_add_u32 s84, s48, 0xed7ca00
	v_readlane_b32 s6, v252, 31
	v_readlane_b32 s7, v252, 32
	v_readlane_b32 s8, v252, 33
	v_readlane_b32 s9, v252, 34
	v_readlane_b32 s11, v252, 36
	v_readlane_b32 s12, v252, 37
	v_readlane_b32 s13, v252, 38
	v_readlane_b32 s14, v252, 39
	v_readlane_b32 s15, v252, 40
	v_writelane_b32 v252, s2, 41
	s_addc_u32 s85, s49, 0
	s_add_u32 s86, s48, 0xed7cb00
	v_writelane_b32 v252, s3, 42
	v_writelane_b32 v252, s0, 43
	s_addc_u32 s87, s49, 0
	v_mul_f32_e32 v0, 0x4f7ffffe, v0
	v_writelane_b32 v252, s1, 44
	s_add_u32 s0, s48, 0xed7cc00
	s_addc_u32 s1, s49, 0
	v_writelane_b32 v252, s0, 45
	v_cvt_u32_f32_e32 v0, v0
	v_mov_b32_e32 v196, 0x358637bd
	v_writelane_b32 v252, s1, 46
	s_add_u32 s0, s48, 0xed7cd00
	s_addc_u32 s1, s49, 0
	v_writelane_b32 v252, s0, 47
	v_readfirstlane_b32 s3, v0
	v_mbcnt_lo_u32_b32 v0, -1, 0
	v_writelane_b32 v252, s1, 48
	s_add_u32 s0, s48, 0xed7ce00
	s_addc_u32 s1, s49, 0
	v_writelane_b32 v252, s0, 49
	v_mbcnt_hi_u32_b32 v200, -1, v0
	v_mov_b32_e32 v199, 0x10000
	v_writelane_b32 v252, s1, 50
	s_add_u32 s0, s48, 0xed7cf00
	s_addc_u32 s1, s49, 0
	v_writelane_b32 v252, s0, 51
	v_mov_b32_e32 v201, 0x18000
	v_mov_b32_e32 v197, 0x3e38aa3b
	v_writelane_b32 v252, s1, 52
	s_add_u32 s0, s48, 0xed7d000
	s_addc_u32 s1, s49, 0
	v_writelane_b32 v252, s0, 53
	v_mov_b32_e32 v198, 0x900
	v_mov_b32_e32 v206, 0x20000
	v_writelane_b32 v252, s1, 54
	s_add_u32 s0, s48, 0xed7d100
	s_addc_u32 s1, s49, 0
	v_writelane_b32 v252, s0, 55
	v_mov_b32_e32 v207, 0x30000
	v_mov_b32_e32 v210, 0x42000
	v_writelane_b32 v252, s1, 56
	s_add_u32 s0, s48, 0xed7d200
	s_addc_u32 s1, s49, 0
	v_writelane_b32 v252, s0, 57
	v_mov_b32_e32 v211, 0x600
	v_mov_b32_e32 v213, 0x41b17218
	v_writelane_b32 v252, s1, 58
	s_add_u32 s0, s48, 0xed7d300
	s_addc_u32 s1, s49, 0
	v_writelane_b32 v252, s0, 59
	s_movk_i32 s91, 0x90
	s_nop 0
	v_writelane_b32 v252, s1, 60
	s_add_u32 s0, s48, 0xed7f400
	s_addc_u32 s1, s49, 0
	v_writelane_b32 v252, s0, 61
	s_barrier
	s_nop 0
	v_writelane_b32 v252, s1, 62
	s_add_u32 s0, s48, 0xed7f500
	s_addc_u32 s1, s49, 0
	v_writelane_b32 v252, s0, 63
	s_nop 1
	v_writelane_b32 v254, s1, 0
	s_add_u32 s0, s48, 0x7f3c000
	v_writelane_b32 v254, s0, 1
	s_addc_u32 s0, s49, 0
	v_writelane_b32 v254, s0, 2
	s_add_u32 s0, s48, 0x373c000
	s_addc_u32 s1, s49, 0
	s_add_u32 s12, s48, 0x5b3c000
	v_writelane_b32 v254, s0, 3
	s_addc_u32 s13, s49, 0
	s_nop 0
	v_writelane_b32 v254, s1, 4
	s_add_u32 s0, s48, 0xa33c000
	v_writelane_b32 v254, s0, 5
	s_addc_u32 s0, s49, 0
	s_add_i32 s4, s20, 0x80
	v_writelane_b32 v254, s0, 6
	s_add_u32 s0, s48, 0x2e3c000
	v_writelane_b32 v254, s0, 7
	s_addc_u32 s0, s49, 0
	v_writelane_b32 v254, s0, 8
	s_add_u32 s0, s48, 0x493c000
	v_writelane_b32 v254, s0, 9
	s_addc_u32 s0, s49, 0
	s_add_i32 s2, s20, 0x180
	v_writelane_b32 v254, s0, 10
	s_add_u32 s0, s48, 0x805c000
	s_addc_u32 s1, s49, 0
	v_writelane_b32 v254, s0, 11
	s_nop 1
	v_writelane_b32 v254, s1, 12
	s_add_u32 s0, s48, 0xaac000
	s_addc_u32 s1, s49, 0
	v_writelane_b32 v254, s0, 13
	s_nop 1
	v_writelane_b32 v254, s1, 14
	s_add_u32 s0, s48, 0xc97c000
	s_addc_u32 s1, s49, 0
	v_writelane_b32 v254, s0, 15
	s_cmpk_lt_i32 s20, 0x400
	s_nop 0
	v_writelane_b32 v254, s1, 16
	s_cselect_b64 s[0:1], -1, 0
	v_writelane_b32 v254, s0, 17
	s_cmpk_lt_i32 s20, 0x4c0
	s_nop 0
	v_writelane_b32 v254, s1, 18
	s_cselect_b64 s[0:1], -1, 0
	v_writelane_b32 v254, s0, 19
	s_nop 1
	v_writelane_b32 v254, s1, 20
	s_sub_i32 s0, 0, s50
	s_mul_i32 s0, s0, s3
	s_mul_hi_u32 s0, s3, s0
	s_add_i32 s3, s3, s0
	s_mul_hi_u32 s0, s20, s3
	s_mul_i32 s0, s0, s50
	s_sub_i32 s0, s20, s0
	s_sub_i32 s1, s0, s50
	s_cmp_ge_u32 s0, s50
	s_cselect_b32 s0, s1, s0
	s_sub_i32 s1, s0, s50
	s_cmp_ge_u32 s0, s50
	s_cselect_b32 s11, s1, s0
	s_cmpk_lt_i32 s11, 0x1200
	s_cselect_b64 s[0:1], -1, 0
	s_ashr_i32 s14, s11, 3
	v_writelane_b32 v254, s0, 21
	s_mul_hi_i32 s5, s14, 0x2aaaaaab
	s_lshr_b32 s6, s5, 31
	v_writelane_b32 v254, s1, 22
	s_ashr_i32 s0, s5, 5
	s_add_i32 s1, s0, s6
	s_mul_i32 s0, s1, 0xffffff40
	s_add_i32 s7, s0, s14
	s_mul_hi_i32 s0, s7, 0x2aaaaaab
	s_lshr_b32 s8, s0, 31
	s_add_i32 s0, s0, s8
	s_mul_i32 s8, s0, 6
	s_sub_i32 s8, s7, s8
	s_and_b32 s7, s11, 7
	s_mul_i32 s1, s1, 6
	v_writelane_b32 v254, s7, 23
	s_mul_i32 s7, s7, 18
	s_add_i32 s1, s1, s7
	s_add_i32 s8, s1, s8
	s_ashr_i32 s9, s8, 31
	s_lshl_b64 s[8:9], s[8:9], 18
	s_add_u32 s8, s40, s8
	s_addc_u32 s9, s41, s9
	s_ashr_i32 s1, s0, 31
	s_lshl_b64 s[0:1], s[0:1], 18
	v_writelane_b32 v254, s8, 24
	s_add_u32 s0, s48, s0
	s_addc_u32 s1, s49, s1
	v_writelane_b32 v254, s9, 25
	v_writelane_b32 v254, s0, 26
	s_cmpk_lt_i32 s11, 0xe10
	s_cselect_b64 s[8:9], -1, 0
	v_writelane_b32 v254, s1, 27
	s_mul_hi_i32 s0, s14, 0x1b4e81b5
	s_lshr_b32 s1, s0, 31
	s_ashr_i32 s0, s0, 4
	s_add_i32 s1, s0, s1
	v_writelane_b32 v254, s8, 28
	s_mul_i32 s0, s1, 0xffffff6a
	s_mul_i32 s1, s1, 6
	v_writelane_b32 v254, s9, 29
	s_add_i32 s8, s0, s14
	s_mul_hi_i32 s0, s8, 0x2aaaaaab
	s_lshr_b32 s9, s0, 31
	s_add_i32 s0, s0, s9
	s_mul_i32 s9, s0, 6
	s_sub_i32 s8, s8, s9
	s_add_i32 s1, s1, s7
	s_add_i32 s8, s1, s8
	s_ashr_i32 s9, s8, 31
	s_lshl_b64 s[8:9], s[8:9], 18
	s_add_u32 s8, s40, s8
	s_addc_u32 s9, s41, s9
	v_writelane_b32 v254, s8, 30
	s_ashr_i32 s1, s0, 31
	s_nop 0
	v_writelane_b32 v254, s9, 31
	s_lshl_b64 s[8:9], s[0:1], 18
	s_add_u32 s8, s48, s8
	s_addc_u32 s9, s49, s9
	v_writelane_b32 v254, s8, 32
	s_mul_i32 s1, s51, s50
	s_mul_i32 s1, s1, s33
	v_writelane_b32 v254, s9, 33
	s_lshl_b32 s0, s0, 7
	v_writelane_b32 v254, s1, 34
	s_sub_i32 s0, 0xc40, s0
	v_writelane_b32 v254, s0, 35
	s_cmpk_lt_i32 s11, 0x480
	v_writelane_b32 v254, s11, 36
	s_cselect_b64 s[0:1], -1, 0
	v_writelane_b32 v254, s0, 37
	s_movk_i32 s51, 0xffe0
	s_mov_b32 s33, 0x800000
	v_writelane_b32 v254, s1, 38
	s_ashr_i32 s0, s5, 3
	s_add_i32 s0, s0, s6
	s_mul_i32 s1, s0, 0xffffffd0
	s_add_i32 s1, s1, s14
	s_mul_hi_i32 s5, s1, 0x2aaaaaab
	s_lshr_b32 s6, s5, 31
	s_add_i32 s5, s5, s6
	s_mul_i32 s0, s0, 6
	s_mul_i32 s6, s5, 6
	s_add_i32 s0, s0, s7
	s_sub_i32 s1, s1, s6
	s_add_i32 s0, s0, s1
	v_writelane_b32 v254, s14, 39
	s_mul_hi_i32 s7, s0, 0x42000
	s_mul_i32 s6, s0, 0x42000
	s_mul_i32 s0, s5, 0x60
	s_mul_hi_i32 s9, s0, 0x600
	s_add_u32 s0, s12, s6
	v_writelane_b32 v254, s12, 40
	s_mul_i32 s8, s5, 0x24000
	s_nop 0
	v_writelane_b32 v254, s13, 41
	v_writelane_b32 v254, s6, 42
	s_addc_u32 s1, s13, s7
	s_nop 0
	v_writelane_b32 v254, s7, 43
	v_writelane_b32 v254, s0, 44
	s_nop 1
	v_writelane_b32 v254, s1, 45
	s_add_u32 s0, s18, s8
	v_writelane_b32 v254, s18, 46
	s_nop 1
	v_writelane_b32 v254, s19, 47
	v_writelane_b32 v254, s8, 48
	s_addc_u32 s1, s19, s9
	s_nop 0
	v_writelane_b32 v254, s9, 49
	v_writelane_b32 v254, s0, 50
	s_nop 1
	v_writelane_b32 v254, s1, 51
	s_mul_hi_u32 s0, s4, s3
	s_mul_i32 s0, s0, s50
	s_sub_i32 s0, s4, s0
	s_sub_i32 s1, s0, s50
	s_cmp_ge_u32 s0, s50
	s_cselect_b32 s0, s1, s0
	s_sub_i32 s1, s0, s50
	s_cmp_ge_u32 s0, s50
	s_cselect_b32 s6, s1, s0
	s_cmpk_lt_i32 s6, 0x480
	s_cselect_b64 s[0:1], -1, 0
	v_writelane_b32 v254, s0, 52
	s_nop 1
	v_writelane_b32 v254, s1, 53
	s_ashr_i32 s0, s6, 3
	s_mul_hi_i32 s1, s0, 0x2aaaaaab
	s_lshr_b32 s4, s1, 31
	s_ashr_i32 s1, s1, 3
	s_add_i32 s1, s1, s4
	s_mul_i32 s4, s1, 0xffffffd0
	s_add_i32 s4, s4, s0
	s_mul_hi_i32 s0, s4, 0x2aaaaaab
	s_lshr_b32 s5, s0, 31
	s_add_i32 s0, s0, s5
	s_and_b32 s5, s6, 7
	s_mul_i32 s1, s1, 6
	s_mul_i32 s5, s5, 18
	s_add_i32 s1, s1, s5
	s_mul_i32 s5, s0, 6
	s_sub_i32 s4, s4, s5
	s_add_i32 s1, s1, s4
	v_writelane_b32 v254, s6, 54
	s_mul_hi_i32 s5, s1, 0x42000
	s_mul_i32 s4, s1, 0x42000
	s_add_u32 s1, s48, s4
	v_writelane_b32 v254, s4, 55
	s_nop 1
	v_writelane_b32 v254, s5, 56
	s_addc_u32 s4, s49, s5
	s_add_u32 s6, s1, 0x5b3c600
	s_addc_u32 s7, s4, 0
	s_lshl_b32 s0, s0, 7
	v_writelane_b32 v254, s6, 57
	s_ashr_i32 s1, s0, 31
	s_lshl_b64 s[0:1], s[0:1], 9
	v_writelane_b32 v254, s7, 58
	s_add_u32 s4, s16, s0
	v_writelane_b32 v254, s16, 59
	s_nop 1
	v_writelane_b32 v254, s17, 60
	v_writelane_b32 v254, s0, 61
	s_addc_u32 s5, s17, s1
	s_nop 0
	v_writelane_b32 v254, s1, 62
	s_mul_hi_u32 s0, s2, s3
	s_mul_i32 s0, s0, s50
	s_sub_i32 s0, s2, s0
	s_sub_i32 s1, s0, s50
	s_cmp_ge_u32 s0, s50
	s_cselect_b32 s0, s1, s0
	s_sub_i32 s1, s0, s50
	s_cmp_ge_u32 s0, s50
	s_cselect_b32 s0, s1, s0
	v_writelane_b32 v254, s4, 63
	s_cmpk_lt_i32 s0, 0x480
	s_mul_i32 s2, s50, 12
	v_writelane_b32 v255, s5, 0
	s_cselect_b64 s[4:5], -1, 0
	v_writelane_b32 v255, s4, 1
	s_lshl_b32 s1, s20, 6
	s_ashr_i32 s3, s2, 31
	v_writelane_b32 v255, s5, 2
	v_writelane_b32 v255, s1, 3
	s_add_i32 s1, s10, 0x180
	v_writelane_b32 v255, s1, 4
	s_lshl_b32 s1, s50, 3
	v_writelane_b32 v255, s1, 5
	v_writelane_b32 v255, s10, 6
	s_add_i32 s1, s10, s42
	v_writelane_b32 v255, s1, 7
	v_writelane_b32 v255, s2, 8
	s_ashr_i32 s43, s42, 31
	s_nop 0
	v_writelane_b32 v255, s3, 9
	s_lshl_b64 s[2:3], s[2:3], 11
	v_writelane_b32 v255, s2, 10
	s_add_u32 s1, s48, 0x7f3d100
	s_nop 0
	v_writelane_b32 v255, s3, 11
	v_writelane_b32 v255, s1, 12
	s_addc_u32 s1, s49, 0
	v_writelane_b32 v255, s1, 13
	s_add_i32 s1, s20, 0xfffffc00
	v_writelane_b32 v255, s1, 14
	s_add_u32 s1, s48, 0x5b80000
	v_writelane_b32 v255, s1, 15
	s_addc_u32 s1, s49, 0
	s_add_u32 s2, s48, 0x620080
	v_writelane_b32 v255, s1, 16
	s_addc_u32 s3, s49, 0
	v_writelane_b32 v255, s2, 17
	s_nop 1
	v_writelane_b32 v255, s3, 18
	s_add_u32 s2, s48, 0x740080
	s_addc_u32 s3, s49, 0
	v_writelane_b32 v255, s2, 19
	s_lshl_b32 s1, s20, 8
	s_nop 0
	v_writelane_b32 v255, s3, 20
	v_writelane_b32 v255, s1, 21
	s_lshl_b32 s1, s50, 8
	v_writelane_b32 v255, s1, 22
	s_add_u32 s1, s48, 0x2e42000
	v_writelane_b32 v255, s1, 23
	s_addc_u32 s1, s49, 0
	v_writelane_b32 v255, s1, 24
	s_add_u32 s1, s48, 0x493c100
	v_writelane_b32 v255, s1, 25
	s_addc_u32 s1, s49, 0
	v_writelane_b32 v255, s1, 26
	s_add_u32 s1, s48, 0x2ea2000
	v_writelane_b32 v255, s1, 27
	s_addc_u32 s1, s49, 0
	v_writelane_b32 v255, s1, 28
	s_add_i32 s1, s20, 0xfffffb80
	v_writelane_b32 v255, s1, 29
	s_add_u32 s1, s48, 0x493d100
	v_writelane_b32 v255, s1, 30
	s_addc_u32 s1, s49, 0
	v_writelane_b32 v255, s1, 31
	s_add_i32 s1, 0, 0x12000
	v_writelane_b32 v255, s1, 32
	s_add_i32 s1, 0, 0x12004
	v_writelane_b32 v255, s1, 33
	s_add_i32 s1, 0, 0xb000
	v_writelane_b32 v255, s1, 34
	s_add_i32 s1, 0, 0xb190
	v_writelane_b32 v255, s1, 35
	s_add_i32 s1, 0, 0x10800
	v_writelane_b32 v255, s1, 36
	v_writelane_b32 v255, s0, 37
	s_sub_i32 s0, 0x47, s0
	v_writelane_b32 v255, s0, 38
	s_add_i32 s0, 0, 0x11c00
	v_writelane_b32 v255, s0, 39
	s_mov_b32 s0, 0
	s_mov_b32 s1, 0
	v_writelane_b32 v255, s0, 40
	s_nop 1
	v_writelane_b32 v255, s1, 41
	v_writelane_b32 v255, s48, 42
	s_nop 1
	v_writelane_b32 v255, s49, 43
	v_writelane_b32 v255, s50, 44
	v_writelane_b32 v255, s51, 45
	v_writelane_b32 v255, s52, 46
	s_nop 1
	v_writelane_b32 v255, s53, 47
	v_writelane_b32 v255, s34, 48
	s_nop 1
	v_writelane_b32 v255, s35, 49
	v_writelane_b32 v255, s36, 50
	s_nop 1
	v_writelane_b32 v255, s37, 51
	v_writelane_b32 v255, s39, 52
	v_writelane_b32 v255, s40, 53
	s_nop 1
	v_writelane_b32 v255, s41, 54
	v_writelane_b32 v255, s42, 55
	s_nop 1
	v_writelane_b32 v255, s43, 56
	v_writelane_b32 v255, s44, 57
	s_nop 1
	v_writelane_b32 v255, s45, 58
	v_writelane_b32 v255, s46, 59
	s_nop 1
	v_writelane_b32 v255, s47, 60
	v_writelane_b32 v255, s58, 61
	s_nop 1
	v_writelane_b32 v255, s59, 62
	v_writelane_b32 v255, s76, 63
	s_nop 1
	v_writelane_b32 v253, s77, 0
	v_writelane_b32 v253, s78, 1
	s_nop 1
	v_writelane_b32 v253, s79, 2
	v_writelane_b32 v253, s80, 3
	s_nop 1
	v_writelane_b32 v253, s81, 4
	v_writelane_b32 v253, s82, 5
	s_nop 1
	v_writelane_b32 v253, s83, 6
	v_writelane_b32 v253, s84, 7
	s_nop 1
	v_writelane_b32 v253, s85, 8
	v_writelane_b32 v253, s86, 9
	s_nop 1
	v_writelane_b32 v253, s87, 10
	v_writelane_b32 v253, s38, 11
	s_branch .LBB0_88
